# non-temporal (nt) cache policy on the read-once row loads of P1 (both layers) and P6
# speedup vs baseline: 1.0697x; 1.0105x over previous
.Lp1_skip0:
	v_add_u32_e32 v25, 0xffffc000, v30
	v_ashrrev_i32_e32 v31, 31, v30
	v_cmp_gt_i32_e64 s[0:1], s53, v30
	v_mov_b32_e32 v2, s19
	v_mov_b32_e32 v3, s17
	v_cndmask_b32_e64 v1, 0, v31, s[0:1]
	v_cndmask_b32_e64 v0, v25, v30, s[0:1]
	v_cndmask_b32_e64 v3, v2, v3, s[0:1]
	v_mov_b32_e32 v2, s18
	v_mov_b32_e32 v4, s16
	v_cndmask_b32_e64 v2, v2, v4, s[0:1]
	v_lshlrev_b64 v[0:1], 12, v[0:1]
	v_lshl_add_u64 v[0:1], v[2:3], 0, v[0:1]
	v_lshl_add_u64 v[0:1], v[0:1], 0, v[18:19]
	global_load_dwordx4 v[12:15], v[0:1], off nt
	global_load_dwordx4 v[8:11], v[0:1], off offset:16 nt
	global_load_dwordx4 v[4:7], v[0:1], off offset:2048 nt
	s_nop 0
	global_load_dwordx4 v[0:3], v[0:1], off offset:2064 nt
	v_and_b32_e32 v32, 0x7ff, v30
	v_and_b32_e32 v33, 3, v30
	v_cmp_eq_u32_e64 s[2:3], s76, v32
	v_lshrrev_b32_e32 v25, 2, v25
	v_ashrrev_i32_e32 v27, 11, v30
	v_cndmask_b32_e64 v32, 0, 1, s[2:3]
	v_cmp_eq_u32_e64 s[2:3], 3, v33
	v_add_u32_e32 v25, 8, v25
	v_cndmask_b32_e64 v34, v25, v27, s[0:1]
	v_cndmask_b32_e64 v33, 0, 1, s[2:3]
	v_cndmask_b32_e64 v32, v33, v32, s[0:1]
	v_and_b32_e32 v25, 1, v32
	v_cmp_eq_u32_e64 s[2:3], 1, v25
	v_mov_b32_e32 v29, v19
	v_mov_b32_e32 v35, v19
	s_waitcnt vmcnt(3)
	v_mov_b32_e32 v36, v13
	s_waitcnt vmcnt(2)
	v_mov_b32_e32 v37, v9
	v_mov_b32_e32 v32, v12
	v_mov_b32_e32 v33, v8
	s_waitcnt vmcnt(1)
	v_mov_b32_e32 v48, v5
	s_waitcnt vmcnt(0)
	v_mov_b32_e32 v49, v1
	v_pk_mul_f32 v[36:37], v[36:37], v[36:37]
	v_mov_b32_e32 v38, v14
	v_mov_b32_e32 v39, v10
	v_mov_b32_e32 v46, v4
	v_mov_b32_e32 v47, v0
	v_pk_mul_f32 v[48:49], v[48:49], v[48:49]
	v_pk_fma_f32 v[32:33], v[32:33], v[32:33], v[36:37]
	v_mov_b32_e32 v40, v15
	v_mov_b32_e32 v41, v11
	v_mov_b32_e32 v50, v6
	v_mov_b32_e32 v51, v2
	v_pk_fma_f32 v[36:37], v[46:47], v[46:47], v[48:49]
	v_pk_fma_f32 v[32:33], v[38:39], v[38:39], v[32:33]
	v_mov_b32_e32 v52, v7
	v_mov_b32_e32 v53, v3
	v_pk_fma_f32 v[36:37], v[50:51], v[50:51], v[36:37]
	v_pk_fma_f32 v[32:33], v[40:41], v[40:41], v[32:33]
	v_pk_fma_f32 v[36:37], v[52:53], v[52:53], v[36:37]
	v_add_f32_e32 v25, v32, v33
	v_add_f32_e32 v25, v25, v36
	v_add_f32_e32 v25, v25, v37
	v_mov_b64_e32 v[32:33], 0
	s_nop 0
	v_add_f32_dpp v25, v25, v25 row_ror:8 row_mask:0xf bank_mask:0xf bound_ctrl:1
	s_nop 1
	v_add_f32_dpp v25, v25, v25 row_ror:4 row_mask:0xf bank_mask:0xf bound_ctrl:1
	s_nop 1
	v_add_f32_dpp v25, v25, v25 row_ror:2 row_mask:0xf bank_mask:0xf bound_ctrl:1
	s_nop 1
	v_add_f32_dpp v25, v25, v25 row_ror:1 row_mask:0xf bank_mask:0xf bound_ctrl:1
	s_nop 1
	v_mov_b32_dpp v29, v25 row_bcast:15 row_mask:0xa bank_mask:0xf
	v_add_f32_e32 v25, v25, v29
	s_nop 1
	v_mov_b32_dpp v35, v25 row_bcast:31 row_mask:0xc bank_mask:0xf
	v_add_f32_e32 v25, v25, v35
	s_nop 0
	v_readlane_b32 s12, v25, 63
	s_and_saveexec_b64 s[10:11], s[2:3]
	s_cbranch_execz .LBB0_137
	v_cmp_lt_i32_e64 s[0:1], 7, v34
	s_and_saveexec_b64 s[34:35], s[0:1]
	s_xor_b64 s[0:1], exec, s[34:35]
	v_add_u32_e32 v32, -8, v34
	v_mov_b32_e32 v33, v19
	v_lshlrev_b64 v[32:33], 12, v[32:33]
	v_lshl_add_u64 v[32:33], s[4:5], 0, v[32:33]
	s_andn2_saveexec_b64 s[0:1], s[0:1]
	v_ashrrev_i32_e32 v35, 31, v34
	v_lshlrev_b64 v[32:33], 12, v[34:35]
	v_lshl_add_u64 v[32:33], s[6:7], 0, v[32:33]
	s_or_b64 exec, exec, s[0:1]

.LBB0_745:
	v_mov_b32_e32 v0, 2
	s_and_saveexec_b64 s[72:73], s[0:1]
	s_cbranch_execz .LBB0_765
	s_movk_i32 s0, 0x4200
	v_cmp_gt_i32_e64 s[0:1], s0, v48
	s_and_saveexec_b64 s[2:3], s[0:1]
	s_xor_b64 s[80:81], exec, s[2:3]
	s_cbranch_execz .LBB0_762
	s_movk_i32 s0, 0x4000
	v_add_u32_e32 v0, 0xffffc000, v48
	v_cmp_gt_i32_e64 s[2:3], s0, v48
	v_lshrrev_b32_e32 v1, 2, v0
	v_ashrrev_i32_e32 v49, 31, v48
	v_mov_b32_e32 v2, s19
	v_mov_b32_e32 v3, s17
	v_add_u32_e32 v16, 8, v1
	v_cndmask_b32_e64 v1, 0, v49, s[2:3]
	v_cndmask_b32_e64 v0, v0, v48, s[2:3]
	v_cndmask_b32_e64 v3, v2, v3, s[2:3]
	v_mov_b32_e32 v2, s18
	v_mov_b32_e32 v4, s16
	v_cndmask_b32_e64 v2, v2, v4, s[2:3]
	v_lshlrev_b64 v[0:1], 12, v[0:1]
	v_ashrrev_i32_e32 v17, 11, v48
	v_lshl_add_u64 v[0:1], v[2:3], 0, v[0:1]
	v_cndmask_b32_e64 v50, v16, v17, s[2:3]
	v_lshlrev_b64 v[16:17], 12, v[48:49]
	v_lshl_add_u64 v[4:5], v[0:1], 0, v[26:27]
	v_lshl_add_u64 v[56:57], v[38:39], 0, v[16:17]
	global_load_dwordx4 v[8:11], v[4:5], off offset:16 nt
	global_load_dwordx4 v[12:15], v[4:5], off nt
	global_load_dwordx4 v[0:3], v[4:5], off offset:2064 nt
	s_nop 0
	global_load_dwordx4 v[4:7], v[4:5], off offset:2048 nt
	v_mov_b32_e32 v45, v27
	global_load_dwordx4 v[52:55], v[56:57], off nt
	v_mov_b32_e32 v47, v27
	s_waitcnt vmcnt(0)
	v_cvt_f32_f16_sdwa v19, v52 dst_sel:DWORD dst_unused:UNUSED_PAD src0_sel:WORD_1
	v_cvt_f32_f16_sdwa v17, v54 dst_sel:DWORD dst_unused:UNUSED_PAD src0_sel:WORD_1
	v_cvt_f32_f16_e32 v18, v52
	v_cvt_f32_f16_e32 v16, v54
	v_cvt_f32_f16_e32 v22, v53
	v_cvt_f32_f16_e32 v20, v55
	v_cvt_f32_f16_sdwa v23, v53 dst_sel:DWORD dst_unused:UNUSED_PAD src0_sel:WORD_1
	v_cvt_f32_f16_sdwa v21, v55 dst_sel:DWORD dst_unused:UNUSED_PAD src0_sel:WORD_1
	v_mov_b32_e32 v54, v19
	v_mov_b32_e32 v55, v17
	v_mov_b32_e32 v52, v18
	v_mov_b32_e32 v53, v16
	v_pk_mul_f32 v[54:55], v[54:55], v[54:55]
	s_nop 0
	v_pk_fma_f32 v[52:53], v[52:53], v[52:53], v[54:55]
	v_mov_b32_e32 v54, v22
	v_mov_b32_e32 v55, v20
	v_pk_fma_f32 v[52:53], v[54:55], v[54:55], v[52:53]
	v_mov_b32_e32 v54, v23
	v_mov_b32_e32 v55, v21
	v_pk_fma_f32 v[60:61], v[54:55], v[54:55], v[52:53]
	global_load_dwordx4 v[52:55], v[56:57], off offset:1024 nt
	v_add_f32_e32 v43, v60, v61
	s_waitcnt vmcnt(0)
	v_cvt_f32_f16_sdwa v57, v52 dst_sel:DWORD dst_unused:UNUSED_PAD src0_sel:WORD_1
	v_cvt_f32_f16_e32 v58, v53
	v_cvt_f32_f16_sdwa v59, v53 dst_sel:DWORD dst_unused:UNUSED_PAD src0_sel:WORD_1
	v_cvt_f32_f16_sdwa v53, v54 dst_sel:DWORD dst_unused:UNUSED_PAD src0_sel:WORD_1
	v_cvt_f32_f16_e32 v56, v52
	v_cvt_f32_f16_e32 v52, v54
	v_cvt_f32_f16_e32 v54, v55
	v_cvt_f32_f16_sdwa v55, v55 dst_sel:DWORD dst_unused:UNUSED_PAD src0_sel:WORD_1
	v_mov_b32_e32 v64, v57
	v_mov_b32_e32 v65, v53
	v_mov_b32_e32 v62, v56
	v_mov_b32_e32 v63, v52
	v_pk_mul_f32 v[64:65], v[64:65], v[64:65]
	s_nop 0
	v_pk_fma_f32 v[62:63], v[62:63], v[62:63], v[64:65]
	v_mov_b32_e32 v64, v58
	v_mov_b32_e32 v65, v54
	v_pk_fma_f32 v[62:63], v[64:65], v[64:65], v[62:63]
	v_mov_b32_e32 v64, v59
	v_mov_b32_e32 v65, v55
	v_pk_fma_f32 v[62:63], v[64:65], v[64:65], v[62:63]
	s_nop 0
	v_add_f32_e32 v43, v43, v62
	v_add_f32_e32 v43, v43, v63
	s_nop 1
	v_add_f32_dpp v43, v43, v43 row_ror:8 row_mask:0xf bank_mask:0xf bound_ctrl:1
	s_nop 1
	v_add_f32_dpp v43, v43, v43 row_ror:4 row_mask:0xf bank_mask:0xf bound_ctrl:1
	s_nop 1
	v_add_f32_dpp v43, v43, v43 row_ror:2 row_mask:0xf bank_mask:0xf bound_ctrl:1
	s_nop 1
	v_add_f32_dpp v43, v43, v43 row_ror:1 row_mask:0xf bank_mask:0xf bound_ctrl:1
	s_nop 1
	v_mov_b32_dpp v45, v43 row_bcast:15 row_mask:0xa bank_mask:0xf
	v_add_f32_e32 v43, v43, v45
	v_mov_b32_e32 v45, v27
	s_nop 1
	v_mov_b32_dpp v45, v43 row_bcast:31 row_mask:0xc bank_mask:0xf
	v_add_f32_e32 v43, v43, v45
	s_nop 0
	v_readlane_b32 s0, v43, 63
	s_nop 1
	v_fma_f32 v43, s0, v71, v70
	v_cmp_gt_f32_e64 s[0:1], s48, v43
	v_mul_f32_e32 v45, 0x4b800000, v43
	s_nop 0
	v_cndmask_b32_e64 v43, v43, v45, s[0:1]
	v_rsq_f32_e32 v43, v43
	s_nop 0
	v_mul_f32_e32 v45, 0x45800000, v43
	v_cndmask_b32_e64 v68, v43, v45, s[0:1]
	v_readlane_b32 s0, v250, 6
	v_readlane_b32 s1, v250, 7
	v_pk_mul_f32 v[22:23], v[22:23], v[68:69] op_sel_hi:[1,0]
	v_pk_mul_f32 v[18:19], v[18:19], v[68:69] op_sel_hi:[1,0]
	v_mov_b64_e32 v[60:61], s[0:1]
	v_mad_i64_i32 v[60:61], s[0:1], v50, s49, v[60:61]
	s_mov_b64 s[0:1], 0x2000
	s_nop 0
	v_lshl_add_u64 v[80:81], v[60:61], 0, s[0:1]
	global_load_dwordx4 v[60:63], v[28:29], off offset:16
	global_load_dwordx4 v[64:67], v[28:29], off
	v_lshl_add_u64 v[76:77], v[80:81], 0, v[26:27]
	global_load_dwordx4 v[72:75], v[76:77], off offset:16
	s_nop 0
	global_load_dwordx4 v[76:79], v[76:77], off
	v_pk_mul_f32 v[56:57], v[56:57], v[68:69] op_sel_hi:[1,0]
	v_pk_mul_f32 v[58:59], v[58:59], v[68:69] op_sel_hi:[1,0]
	s_movk_i32 s0, 0x7ff
	s_waitcnt vmcnt(2)
	v_pk_mul_f32 v[18:19], v[64:65], v[18:19]
	v_pk_mul_f32 v[22:23], v[66:67], v[22:23]
	s_waitcnt vmcnt(0)
	v_pk_fma_f32 v[66:67], v[76:77], v[18:19], v[12:13]
	v_pk_fma_f32 v[64:65], v[78:79], v[22:23], v[14:15]
	v_pk_mul_f32 v[12:13], v[20:21], v[68:69] op_sel_hi:[1,0]
	v_pk_mul_f32 v[14:15], v[16:17], v[68:69] op_sel_hi:[1,0]
	v_pk_mul_f32 v[12:13], v[62:63], v[12:13]
	v_pk_mul_f32 v[14:15], v[60:61], v[14:15]
	v_pk_fma_f32 v[60:61], v[74:75], v[12:13], v[10:11]
	v_pk_fma_f32 v[62:63], v[72:73], v[14:15], v[8:9]
	global_load_dwordx4 v[8:11], v[28:29], off offset:2064
	global_load_dwordx4 v[12:15], v[28:29], off offset:2048
	v_lshl_add_u64 v[20:21], v[80:81], 0, v[46:47]
	global_load_dwordx4 v[16:19], v[20:21], off offset:16
	s_nop 0
	global_load_dwordx4 v[20:23], v[20:21], off
	s_waitcnt vmcnt(2)
	v_pk_mul_f32 v[12:13], v[12:13], v[56:57]
	v_pk_mul_f32 v[14:15], v[14:15], v[58:59]
	s_waitcnt vmcnt(0)
	v_pk_fma_f32 v[20:21], v[20:21], v[12:13], v[4:5]
	v_pk_mul_f32 v[4:5], v[54:55], v[68:69] op_sel_hi:[1,0]
	v_pk_fma_f32 v[22:23], v[22:23], v[14:15], v[6:7]
	v_pk_mul_f32 v[6:7], v[52:53], v[68:69] op_sel_hi:[1,0]
	v_pk_mul_f32 v[4:5], v[10:11], v[4:5]
	v_pk_mul_f32 v[6:7], v[8:9], v[6:7]
	v_pk_fma_f32 v[12:13], v[18:19], v[4:5], v[2:3]
	v_mov_b32_e32 v2, v67
	v_mov_b32_e32 v3, v63
	v_pk_fma_f32 v[14:15], v[16:17], v[6:7], v[0:1]
	v_mov_b32_e32 v0, v66
	v_mov_b32_e32 v1, v62
	v_pk_mul_f32 v[2:3], v[2:3], v[2:3]
	v_mov_b32_e32 v4, v15
	v_pk_fma_f32 v[0:1], v[0:1], v[0:1], v[2:3]
	v_mov_b32_e32 v2, v64
	v_mov_b32_e32 v3, v60
	v_pk_fma_f32 v[0:1], v[2:3], v[2:3], v[0:1]
	v_mov_b32_e32 v2, v65
	v_mov_b32_e32 v3, v61
	v_mov_b32_e32 v5, v21
	v_pk_fma_f32 v[0:1], v[2:3], v[2:3], v[0:1]
	v_mov_b32_e32 v2, v14
	v_mov_b32_e32 v3, v20
	v_pk_mul_f32 v[4:5], v[4:5], v[4:5]
	v_add_f32_e32 v0, v0, v1
	v_pk_fma_f32 v[2:3], v[2:3], v[2:3], v[4:5]
	v_mov_b32_e32 v4, v12
	v_mov_b32_e32 v5, v22
	v_pk_fma_f32 v[2:3], v[4:5], v[4:5], v[2:3]
	v_mov_b32_e32 v4, v13
	v_mov_b32_e32 v5, v23
	v_pk_fma_f32 v[2:3], v[4:5], v[4:5], v[2:3]
	v_mov_b32_e32 v1, v27
	v_add_f32_e32 v0, v3, v0
	v_add_f32_e32 v0, v2, v0
	v_mov_b64_e32 v[16:17], 0
	s_nop 0
	v_add_f32_dpp v0, v0, v0 row_ror:8 row_mask:0xf bank_mask:0xf bound_ctrl:1
	s_nop 1
	v_add_f32_dpp v0, v0, v0 row_ror:4 row_mask:0xf bank_mask:0xf bound_ctrl:1
	s_nop 1
	v_add_f32_dpp v0, v0, v0 row_ror:2 row_mask:0xf bank_mask:0xf bound_ctrl:1
	s_nop 1
	v_add_f32_dpp v0, v0, v0 row_ror:1 row_mask:0xf bank_mask:0xf bound_ctrl:1
	s_nop 1
	v_mov_b32_dpp v1, v0 row_bcast:15 row_mask:0xa bank_mask:0xf
	v_add_f32_e32 v0, v0, v1
	v_mov_b32_e32 v1, v27
	s_nop 1
	v_mov_b32_dpp v1, v0 row_bcast:31 row_mask:0xc bank_mask:0xf
	v_add_f32_e32 v0, v0, v1
	s_nop 0
	v_readlane_b32 s10, v0, 63
	v_and_b32_e32 v0, 0x7ff, v48
	v_cmp_eq_u32_e64 s[0:1], s0, v0
	v_and_b32_e32 v0, 3, v48
	v_cmp_eq_u32_e64 s[4:5], 3, v0
	v_cndmask_b32_e64 v0, 0, 1, s[0:1]
	s_nop 0
	v_cndmask_b32_e64 v1, 0, 1, s[4:5]
	v_cndmask_b32_e64 v0, v1, v0, s[2:3]
	v_and_b32_e32 v0, 1, v0
	v_cmp_eq_u32_e64 s[2:3], 1, v0
	s_and_saveexec_b64 s[4:5], s[2:3]
	s_cbranch_execz .LBB0_753
	v_ashrrev_i32_e32 v51, 31, v50
	v_cmp_lt_i32_e64 s[0:1], 7, v50
	s_and_saveexec_b64 s[42:43], s[0:1]
	s_xor_b64 s[0:1], exec, s[42:43]
	v_add_u32_e32 v0, -8, v50
	v_mov_b32_e32 v1, v27
	v_lshlrev_b64 v[0:1], 12, v[0:1]
	v_lshl_add_u64 v[16:17], s[8:9], 0, v[0:1]
	s_andn2_saveexec_b64 s[0:1], s[0:1]
	v_lshlrev_b64 v[0:1], 12, v[50:51]
	v_lshl_add_u64 v[16:17], s[52:53], 0, v[0:1]
	s_or_b64 exec, exec, s[0:1]

.LBB0_1360:
	s_movk_i32 s8, 0x4200
	v_cmp_gt_i32_e32 vcc, s8, v48
	s_and_saveexec_b64 s[0:1], vcc
	s_cbranch_execz .LBB0_1369
	s_movk_i32 s9, 0x4000
	v_cmp_gt_i32_e32 vcc, s9, v48
	v_mov_b32_e32 v2, s19
	v_mov_b32_e32 v3, s17
	v_add_u32_e32 v0, 0xffffc000, v48
	v_ashrrev_i32_e32 v49, 31, v48
	v_cndmask_b32_e32 v3, v2, v3, vcc
	v_mov_b32_e32 v2, s18
	v_mov_b32_e32 v4, s16
	v_cndmask_b32_e32 v1, 0, v49, vcc
	v_cndmask_b32_e32 v0, v0, v48, vcc
	v_cndmask_b32_e32 v2, v2, v4, vcc
	v_lshlrev_b32_e32 v4, 2, v154
	v_lshlrev_b64 v[0:1], 12, v[0:1]
	v_and_b32_e32 v10, 0xfc, v4
	v_mov_b32_e32 v33, 0
	v_lshl_add_u64 v[0:1], v[2:3], 0, v[0:1]
	v_lshlrev_b64 v[2:3], 12, v[48:49]
	v_lshlrev_b32_e32 v32, 2, v10
	v_lshl_add_u64 v[2:3], s[74:75], 0, v[2:3]
	v_lshl_add_u64 v[12:13], v[0:1], 0, v[32:33]
	v_lshlrev_b32_e32 v14, 1, v10
	v_mov_b32_e32 v15, v33
	v_lshl_add_u64 v[20:21], v[2:3], 0, v[14:15]
	global_load_dwordx4 v[28:31], v[12:13], off nt
	global_load_dwordx4 v[16:19], v[12:13], off offset:1024 nt
	global_load_dwordx4 v[4:7], v[12:13], off offset:2048 nt
	global_load_dwordx4 v[0:3], v[12:13], off offset:3072 nt
	global_load_dwordx2 v[90:91], v[20:21], off nt
	global_load_dwordx2 v[86:87], v[20:21], off offset:512 nt
	global_load_dwordx2 v[74:75], v[20:21], off offset:1024 nt
	global_load_dwordx2 v[70:71], v[20:21], off offset:1536 nt
	global_load_dwordx2 v[88:89], v[20:21], off offset:2048 nt
	global_load_dwordx2 v[84:85], v[20:21], off offset:2560 nt
	global_load_dwordx2 v[72:73], v[20:21], off offset:3072 nt
	global_load_dwordx2 v[68:69], v[20:21], off offset:3584 nt
	global_load_dword v130, v[12:13], off
	global_load_dword v131, v[12:13], off
	global_load_dword v132, v[12:13], off
	global_load_dword v133, v[12:13], off
	s_mov_b32 s93, -1
	v_lshl_add_u64 v[36:37], s[40:41], 0, v[32:33]
	s_mov_b64 s[0:1], 0x1000
	v_lshl_add_u64 v[38:39], v[36:37], 0, s[0:1]
	s_mov_b64 s[0:1], 0x1400
	v_lshl_add_u64 v[40:41], v[36:37], 0, s[0:1]
	s_mov_b64 s[0:1], 0x1800
	v_lshl_add_u64 v[42:43], v[36:37], 0, s[0:1]
	s_mov_b64 s[0:1], 0x1c00
	v_lshl_add_u64 v[44:45], v[36:37], 0, s[0:1]
	v_readlane_b32 s0, v250, 12
	s_mov_b32 s10, 1
	v_lshl_add_u64 v[34:35], s[74:75], 0, v[32:33]
	v_lshl_add_u32 v9, s0, 3, v8
	v_readlane_b32 s0, v250, 13
	s_lshl_b32 s0, s0, 3
	v_lshl_add_u64 v[46:47], s[74:75], 0, v[14:15]
	v_subrev_u32_e32 v9, s0, v9
	v_add_u32_e32 v9, 8, v9
	v_readlane_b32 s0, v250, 23
	v_mul_lo_u32 v9, s13, v9
	s_add_i32 s0, s20, s0
	v_add_u32_e32 v100, s91, v9
	v_add_u32_e32 v101, s0, v8
	s_mov_b32 s11, 0
	s_mov_b64 s[2:3], 0
	s_movk_i32 s12, 0x41ff
	v_mov_b32_e32 v102, 0x358637bd
	s_mov_b32 s13, 0x800000
	s_movk_i32 s14, 0x6000
	v_lshlrev_b32_e32 v32, 2, v10
	s_mov_b64 s[4:5], 0x2000
	s_mov_b64 s[6:7], 0x5000
	s_movk_i32 s15, 0x2000
	s_movk_i32 s22, 0x5000
	v_mov_b32_e32 v103, 0x3a800000
	s_branch .LBB0_1363

.LBB0_1367:
	v_cmp_lt_i32_e64 s[0:1], s12, v66
	v_cmp_gt_i32_e32 vcc, s8, v66
	s_or_b64 s[2:3], s[0:1], s[2:3]
	s_and_saveexec_b64 s[0:1], vcc
	s_cbranch_execz .Lp6_skip
	v_add_u32_e32 v8, 0xffffc000, v66
	v_ashrrev_i32_e32 v67, 31, v66
	v_cmp_gt_i32_e32 vcc, s9, v66
	v_mov_b32_e32 v10, s19
	v_mov_b32_e32 v11, s17
	v_cndmask_b32_e32 v9, 0, v67, vcc
	v_cndmask_b32_e32 v8, v8, v66, vcc
	v_cndmask_b32_e32 v11, v10, v11, vcc
	v_mov_b32_e32 v10, s18
	v_mov_b32_e32 v12, s16
	v_cndmask_b32_e32 v10, v10, v12, vcc
	v_lshlrev_b64 v[8:9], 12, v[8:9]
	v_lshl_add_u64 v[8:9], v[10:11], 0, v[8:9]
	v_lshlrev_b64 v[10:11], 12, v[66:67]
	v_lshl_add_u64 v[76:77], v[8:9], 0, v[32:33]
	v_lshl_add_u64 v[78:79], v[46:47], 0, v[10:11]
	global_load_dwordx4 v[8:11], v[76:77], off nt
	global_load_dwordx4 v[12:15], v[76:77], off offset:1024 nt
	global_load_dwordx4 v[20:23], v[76:77], off offset:2048 nt
	global_load_dwordx4 v[24:27], v[76:77], off offset:3072 nt
	global_load_dwordx2 v[50:51], v[78:79], off nt
	global_load_dwordx2 v[56:57], v[78:79], off offset:512 nt
	global_load_dwordx2 v[58:59], v[78:79], off offset:1024 nt
	global_load_dwordx2 v[60:61], v[78:79], off offset:1536 nt
	global_load_dwordx2 v[62:63], v[78:79], off offset:2048 nt
	global_load_dwordx2 v[64:65], v[78:79], off offset:2560 nt
	global_load_dwordx2 v[52:53], v[78:79], off offset:3072 nt
	global_load_dwordx2 v[54:55], v[78:79], off offset:3584 nt
	s_waitcnt vmcnt(16)
	s_branch .LBB0_1362
